# loop-edge edit: diff-mixer tile loop pointer increments moved from the post-barrier head to the pre-barrier tail (bit-identical); stacked on v_all2
# baseline (speedup 1.0000x reference)
; template <int MODE> ...
;     ...
;     ATT_LOAD(ATT_TILE(0), kstA, vstA, lfA); ATT_WRITE(ATT_TILE(0), 0, kstA, vstA, lfA);
;     if (nt > 1) ATT_LOAD(ATT_TILE(1), kstB, vstB, lfB);
;     __syncthreads();
;     bool stop = false;
;     for (int it = 0; it < nt; it += 2) {
;         ATT_STEP(it, kstA, vstA, lfA, kstB, vstB, lfB);
;         if (stop || it + 1 >= nt) break;
;         ATT_STEP(it + 1, kstB, vstB, lfB, kstA, vstA, lfA);
;         if (stop) break;
.LBB0_297:
	v_lshl_add_u64 v[180:181], v[180:181], 0, s[64:65]
	v_lshl_add_u64 v[182:183], v[182:183], 0, s[64:65]
	v_lshl_add_u64 v[184:185], v[184:185], 0, s[92:93]
	v_lshl_add_u64 v[186:187], v[186:187], 0, s[92:93]
	s_and_b64 vcc, exec, s[38:39]
	s_waitcnt lgkmcnt(0)
	s_barrier
	s_cbranch_vccz .LBB0_299
	s_mov_b64 s[10:11], s[8:9]
	s_cbranch_execz .LBB0_300
	s_branch .LBB0_301

; template <int MODE> ...
;     ...
;     for (int it = 0; it < nt; it += 2) {
;         ATT_STEP(it, kstA, vstA, lfA, kstB, vstB, lfB);
;         if (stop || it + 1 >= nt) break;
;         ATT_STEP(it + 1, kstB, vstB, lfB, kstA, vstA, lfA);
;         if (stop) break;
;     }
.LBB0_301:
	s_andn2_b64 vcc, exec, s[10:11]
	s_mov_b64 s[10:11], -1
	s_cbranch_vccnz .LBB0_247
	s_add_i32 s2, s2, 2
	s_addk_i32 s29, 0xff80
	s_mov_b64 s[10:11], 0
	s_branch .LBB0_247
